# grid barrier: waiters poll the cross-XCD release word directly (one hop less), on top of previous
# baseline (speedup 1.0000x reference)
; __device__ __forceinline__ unsigned xb_ld(unsigned* p)              { return __hip_atomic_load(p, __ATOMIC_RELAXED, __HIP_MEMORY_SCOPE_AGENT); }
; __device__ __forceinline__ unsigned xb_add(unsigned* p, unsigned v) { return __hip_atomic_fetch_add(p, v, __ATOMIC_RELAXED, __HIP_MEMORY_SCOPE_AGENT); }
; #define XB_SPIN(cond, bar) do { unsigned _sp = 0; while (cond) { __builtin_amdgcn_s_sleep(1); \
;     if ((++_sp & 255u) == 0u) { if (xb_ld(&(bar)[XB_TMO])) break; if (_sp > XB_SPIN_CAP) { atomicAdd(&(bar)[XB_TMO], 1u); break; } } } } while (0)
; __device__ __forceinline__ void xcd_barrier(const XcdBarrier& b) {
;     ...
;         const unsigned old = xb_add(&bar[XB_XSUB(b.x)], 1u);
;         const unsigned gen = old / nloc;
;         if (old + 1u == (gen + 1u) * nloc) {
;             __builtin_amdgcn_fence(__ATOMIC_RELEASE, "agent");
;             asm volatile("s_waitcnt vmcnt(0)" ::: "memory");
;             const unsigned og = xb_add(&bar[XB_TOP], 1u);
;             const unsigned tg = og / nx;
;             if (og + 1u == (tg + 1u) * nx) xb_add(&bar[XB_TOPGEN], 1u);
;             else XB_SPIN(xb_ld(&bar[XB_TOPGEN]) == tg, bar);
;             __builtin_amdgcn_fence(__ATOMIC_ACQUIRE, "agent");
;             xb_add(&bar[XB_XGEN(b.x)], 1u);
;             asm volatile("s_waitcnt vmcnt(0)" ::: "memory");
;         } else {
;             XB_SPIN(xb_ld(&bar[XB_XGEN(b.x)]) == gen, bar);
;             __builtin_amdgcn_fence(__ATOMIC_ACQUIRE, "agent");
;             asm volatile("s_waitcnt vmcnt(0)" ::: "memory");
;         }
.LBB0_42:
	v_readlane_b32 s0, v254, 5
	s_lshl_b32 s0, s0, 8
	v_readlane_b32 s4, v254, 3
	v_readlane_b32 s5, v254, 4
	s_add_u32 s4, s4, s0
	s_addc_u32 s5, s5, 0
	v_mov_b32_e32 v2, 0x1000
	v_mov_b32_e32 v4, 1
	v_sub_u32_e32 v5, 0, v3
	global_atomic_add v4, v2, v4, s[4:5] offset:1024 sc0
	v_cvt_f32_u32_e32 v2, v3
	v_rcp_iflag_f32_e32 v2, v2
	s_nop 0
	v_mul_f32_e32 v2, 0x4f7ffffe, v2
	v_cvt_u32_f32_e32 v2, v2
	v_mul_lo_u32 v5, v5, v2
	v_mul_hi_u32 v5, v2, v5
	v_add_u32_e32 v2, v2, v5
	s_waitcnt vmcnt(0)
	v_mul_hi_u32 v2, v4, v2
	v_mul_lo_u32 v5, v2, v3
	v_sub_u32_e32 v5, v4, v5
	v_add_u32_e32 v6, 1, v2
	v_cmp_ge_u32_e32 vcc, v5, v3
	v_add_u32_e32 v4, 1, v4
	s_nop 0
	v_cndmask_b32_e32 v2, v2, v6, vcc
	v_sub_u32_e32 v6, v5, v3
	v_cndmask_b32_e32 v5, v5, v6, vcc
	v_add_u32_e32 v6, 1, v2
	v_cmp_ge_u32_e32 vcc, v5, v3
	s_nop 1
	v_cndmask_b32_e32 v2, v2, v6, vcc
	v_mul_lo_u32 v5, v3, v2
	v_add_u32_e32 v3, v5, v3
	v_cmp_ne_u32_e32 vcc, v4, v3
	s_and_saveexec_b64 s[0:1], vcc
	s_xor_b64 s[6:7], exec, s[0:1]
	s_cbranch_execz .LBB0_56
	s_waitcnt lgkmcnt(0)
	s_add_u32 s12, s44, 0x7500
	s_addc_u32 s13, s45, 0
	v_mov_b32_e32 v1, 0
	global_load_dword v1, v1, s[12:13] sc1
	s_waitcnt vmcnt(0)
	v_cmp_eq_u32_e32 vcc, v1, v2
	s_and_saveexec_b64 s[8:9], vcc
	s_cbranch_execz .LBB0_55
	s_add_u32 s10, s44, 0x4200
	s_addc_u32 s11, s45, 0
	s_mov_b32 s22, 1
	s_mov_b64 s[14:15], 0
	v_mov_b32_e32 v1, 0
	s_branch .LBB0_46

; __device__ __forceinline__ unsigned xb_ld(unsigned* p)              { return __hip_atomic_load(p, __ATOMIC_RELAXED, __HIP_MEMORY_SCOPE_AGENT); }
; __device__ __forceinline__ unsigned xb_add(unsigned* p, unsigned v) { return __hip_atomic_fetch_add(p, v, __ATOMIC_RELAXED, __HIP_MEMORY_SCOPE_AGENT); }
; #define XB_SPIN(cond, bar) do { unsigned _sp = 0; while (cond) { __builtin_amdgcn_s_sleep(1); \
;     if ((++_sp & 255u) == 0u) { if (xb_ld(&(bar)[XB_TMO])) break; if (_sp > XB_SPIN_CAP) { atomicAdd(&(bar)[XB_TMO], 1u); break; } } } } while (0)
; __device__ __forceinline__ void xcd_barrier(const XcdBarrier& b) {
;     ...
;         const unsigned old = xb_add(&bar[XB_XSUB(b.x)], 1u);
;         const unsigned gen = old / nloc;
;         if (old + 1u == (gen + 1u) * nloc) {
;             __builtin_amdgcn_fence(__ATOMIC_RELEASE, "agent");
;             asm volatile("s_waitcnt vmcnt(0)" ::: "memory");
;             const unsigned og = xb_add(&bar[XB_TOP], 1u);
;             const unsigned tg = og / nx;
;             if (og + 1u == (tg + 1u) * nx) xb_add(&bar[XB_TOPGEN], 1u);
;             else XB_SPIN(xb_ld(&bar[XB_TOPGEN]) == tg, bar);
;             __builtin_amdgcn_fence(__ATOMIC_ACQUIRE, "agent");
;             xb_add(&bar[XB_XGEN(b.x)], 1u);
;             asm volatile("s_waitcnt vmcnt(0)" ::: "memory");
;         } else {
;             XB_SPIN(xb_ld(&bar[XB_XGEN(b.x)]) == gen, bar);
;             __builtin_amdgcn_fence(__ATOMIC_ACQUIRE, "agent");
;             asm volatile("s_waitcnt vmcnt(0)" ::: "memory");
;         }
.LBB0_159:
	v_readlane_b32 s0, v254, 5
	s_lshl_b32 s0, s0, 8
	v_readlane_b32 s4, v254, 3
	v_readlane_b32 s5, v254, 4
	s_add_u32 s4, s4, s0
	s_addc_u32 s5, s5, 0
	v_mov_b32_e32 v2, 0x1000
	v_mov_b32_e32 v4, 1
	v_sub_u32_e32 v5, 0, v3
	global_atomic_add v4, v2, v4, s[4:5] offset:1024 sc0
	v_cvt_f32_u32_e32 v2, v3
	v_rcp_iflag_f32_e32 v2, v2
	s_nop 0
	v_mul_f32_e32 v2, 0x4f7ffffe, v2
	v_cvt_u32_f32_e32 v2, v2
	v_mul_lo_u32 v5, v5, v2
	v_mul_hi_u32 v5, v2, v5
	v_add_u32_e32 v2, v2, v5
	s_waitcnt vmcnt(0)
	v_mul_hi_u32 v2, v4, v2
	v_mul_lo_u32 v5, v2, v3
	v_sub_u32_e32 v5, v4, v5
	v_add_u32_e32 v6, 1, v2
	v_cmp_ge_u32_e32 vcc, v5, v3
	v_add_u32_e32 v4, 1, v4
	s_nop 0
	v_cndmask_b32_e32 v2, v2, v6, vcc
	v_sub_u32_e32 v6, v5, v3
	v_cndmask_b32_e32 v5, v5, v6, vcc
	v_add_u32_e32 v6, 1, v2
	v_cmp_ge_u32_e32 vcc, v5, v3
	s_nop 1
	v_cndmask_b32_e32 v2, v2, v6, vcc
	v_mul_lo_u32 v5, v3, v2
	v_add_u32_e32 v3, v5, v3
	v_cmp_ne_u32_e32 vcc, v4, v3
	s_and_saveexec_b64 s[0:1], vcc
	s_xor_b64 s[6:7], exec, s[0:1]
	s_cbranch_execz .LBB0_173
	s_waitcnt lgkmcnt(0)
	s_add_u32 s12, s44, 0x7500
	s_addc_u32 s13, s45, 0
	v_mov_b32_e32 v1, 0
	global_load_dword v1, v1, s[12:13] sc1
	s_waitcnt vmcnt(0)
	v_cmp_eq_u32_e32 vcc, v1, v2
	s_and_saveexec_b64 s[8:9], vcc
	s_cbranch_execz .LBB0_172
	s_add_u32 s10, s44, 0x4200
	s_addc_u32 s11, s45, 0
	s_mov_b32 s0, 1
	s_mov_b64 s[14:15], 0
	v_mov_b32_e32 v1, 0
	s_branch .LBB0_163

; __device__ __forceinline__ unsigned xb_ld(unsigned* p)              { return __hip_atomic_load(p, __ATOMIC_RELAXED, __HIP_MEMORY_SCOPE_AGENT); }
; __device__ __forceinline__ unsigned xb_add(unsigned* p, unsigned v) { return __hip_atomic_fetch_add(p, v, __ATOMIC_RELAXED, __HIP_MEMORY_SCOPE_AGENT); }
; #define XB_SPIN(cond, bar) do { unsigned _sp = 0; while (cond) { __builtin_amdgcn_s_sleep(1); \
;     if ((++_sp & 255u) == 0u) { if (xb_ld(&(bar)[XB_TMO])) break; if (_sp > XB_SPIN_CAP) { atomicAdd(&(bar)[XB_TMO], 1u); break; } } } } while (0)
; __device__ __forceinline__ void xcd_barrier(const XcdBarrier& b) {
;     ...
;         const unsigned old = xb_add(&bar[XB_XSUB(b.x)], 1u);
;         const unsigned gen = old / nloc;
;         if (old + 1u == (gen + 1u) * nloc) {
;             __builtin_amdgcn_fence(__ATOMIC_RELEASE, "agent");
;             asm volatile("s_waitcnt vmcnt(0)" ::: "memory");
;             const unsigned og = xb_add(&bar[XB_TOP], 1u);
;             const unsigned tg = og / nx;
;             if (og + 1u == (tg + 1u) * nx) xb_add(&bar[XB_TOPGEN], 1u);
;             else XB_SPIN(xb_ld(&bar[XB_TOPGEN]) == tg, bar);
;             __builtin_amdgcn_fence(__ATOMIC_ACQUIRE, "agent");
;             xb_add(&bar[XB_XGEN(b.x)], 1u);
;             asm volatile("s_waitcnt vmcnt(0)" ::: "memory");
;         } else {
;             XB_SPIN(xb_ld(&bar[XB_XGEN(b.x)]) == gen, bar);
;             __builtin_amdgcn_fence(__ATOMIC_ACQUIRE, "agent");
;             asm volatile("s_waitcnt vmcnt(0)" ::: "memory");
;         }
.LBB0_406:
	v_readlane_b32 s0, v254, 5
	s_lshl_b32 s0, s0, 8
	v_readlane_b32 s2, v254, 3
	v_readlane_b32 s3, v254, 4
	s_add_u32 s2, s2, s0
	s_addc_u32 s3, s3, 0
	v_mov_b32_e32 v2, 0x1000
	v_mov_b32_e32 v4, 1
	v_sub_u32_e32 v5, 0, v3
	global_atomic_add v4, v2, v4, s[2:3] offset:1024 sc0
	v_cvt_f32_u32_e32 v2, v3
	v_rcp_iflag_f32_e32 v2, v2
	s_nop 0
	v_mul_f32_e32 v2, 0x4f7ffffe, v2
	v_cvt_u32_f32_e32 v2, v2
	v_mul_lo_u32 v5, v5, v2
	v_mul_hi_u32 v5, v2, v5
	v_add_u32_e32 v2, v2, v5
	s_waitcnt vmcnt(0)
	v_mul_hi_u32 v2, v4, v2
	v_mul_lo_u32 v5, v2, v3
	v_sub_u32_e32 v5, v4, v5
	v_add_u32_e32 v6, 1, v2
	v_cmp_ge_u32_e32 vcc, v5, v3
	v_add_u32_e32 v4, 1, v4
	s_nop 0
	v_cndmask_b32_e32 v2, v2, v6, vcc
	v_sub_u32_e32 v6, v5, v3
	v_cndmask_b32_e32 v5, v5, v6, vcc
	v_add_u32_e32 v6, 1, v2
	v_cmp_ge_u32_e32 vcc, v5, v3
	s_nop 1
	v_cndmask_b32_e32 v2, v2, v6, vcc
	v_mul_lo_u32 v5, v3, v2
	v_add_u32_e32 v3, v5, v3
	v_cmp_ne_u32_e32 vcc, v4, v3
	s_and_saveexec_b64 s[0:1], vcc
	s_xor_b64 s[6:7], exec, s[0:1]
	s_cbranch_execz .LBB0_420
	s_waitcnt lgkmcnt(0)
	s_add_u32 s12, s44, 0x7500
	s_addc_u32 s13, s45, 0
	v_mov_b32_e32 v1, 0
	global_load_dword v1, v1, s[12:13] sc1
	s_waitcnt vmcnt(0)
	v_cmp_eq_u32_e32 vcc, v1, v2
	s_and_saveexec_b64 s[8:9], vcc
	s_cbranch_execz .LBB0_419
	s_add_u32 s10, s44, 0x4200
	s_addc_u32 s11, s45, 0
	s_mov_b32 s0, 1
	s_mov_b64 s[14:15], 0
	v_mov_b32_e32 v1, 0
	s_branch .LBB0_410
